# mixer pass-2 entry-state rebuild (retention, SSD chains): the eight local-state loads per earlier segment issued together with progressive waits
# speedup vs baseline: 1.0151x; 1.0099x over previous
.LBB0_604:
	s_ashr_i32 s23, s22, 31
	s_lshl_b64 s[24:25], s[22:23], 9
	v_lshl_add_u64 v[70:71], v[0:1], 0, s[24:25]
	global_load_dword v3, v[70:71], off
	global_load_dwordx4 v[140:143], v[68:69], off
	v_add_co_u32_e32 v172, vcc, s97, v68
	v_addc_co_u32_e32 v173, vcc, 0, v69, vcc
	global_load_dwordx4 v[144:147], v[172:173], off offset:-4096
	global_load_dwordx4 v[148:151], v[172:173], off
	v_add_co_u32_e32 v174, vcc, s4, v68
	v_addc_co_u32_e32 v175, vcc, 0, v69, vcc
	global_load_dwordx4 v[152:155], v[174:175], off offset:-4096
	global_load_dwordx4 v[156:159], v[174:175], off
	v_add_co_u32_e32 v176, vcc, s5, v68
	v_addc_co_u32_e32 v177, vcc, 0, v69, vcc
	global_load_dwordx4 v[160:163], v[176:177], off offset:-4096
	global_load_dwordx4 v[164:167], v[176:177], off
	v_add_co_u32_e32 v178, vcc, s6, v68
	v_addc_co_u32_e32 v179, vcc, 0, v69, vcc
	global_load_dwordx4 v[168:171], v[178:179], off
	s_waitcnt vmcnt(7)
	s_add_i32 s21, s21, -1
	s_add_i32 s22, s22, 1
	s_cmp_lg_u32 s21, 0
	v_mul_f32_e32 v3, 0x3fb8aa3b, v3
	v_exp_f32_e32 v70, v3
	v_lshlrev_b32_e32 v76, 16, v140
	v_and_b32_e32 v77, 0xffff0000, v140
	v_lshlrev_b32_e32 v72, 16, v141
	v_and_b32_e32 v73, 0xffff0000, v141
	v_pk_fma_f32 v[4:5], v[4:5], v[70:71], v[76:77] op_sel_hi:[1,0,1]
	v_pk_fma_f32 v[6:7], v[6:7], v[70:71], v[72:73] op_sel_hi:[1,0,1]
	v_lshlrev_b32_e32 v72, 16, v142
	v_and_b32_e32 v73, 0xffff0000, v142
	v_lshlrev_b32_e32 v74, 16, v143
	v_and_b32_e32 v75, 0xffff0000, v143
	v_pk_fma_f32 v[10:11], v[10:11], v[70:71], v[74:75] op_sel_hi:[1,0,1]
	v_pk_fma_f32 v[8:9], v[8:9], v[70:71], v[72:73] op_sel_hi:[1,0,1]
	s_waitcnt vmcnt(6)
	v_lshlrev_b32_e32 v78, 16, v144
	v_and_b32_e32 v79, 0xffff0000, v144
	v_lshlrev_b32_e32 v72, 16, v145
	v_and_b32_e32 v73, 0xffff0000, v145
	v_pk_fma_f32 v[14:15], v[14:15], v[70:71], v[72:73] op_sel_hi:[1,0,1]
	v_lshlrev_b32_e32 v72, 16, v146
	v_and_b32_e32 v73, 0xffff0000, v146
	v_lshlrev_b32_e32 v74, 16, v147
	v_and_b32_e32 v75, 0xffff0000, v147
	v_pk_fma_f32 v[18:19], v[18:19], v[70:71], v[74:75] op_sel_hi:[1,0,1]
	v_pk_fma_f32 v[16:17], v[16:17], v[70:71], v[72:73] op_sel_hi:[1,0,1]
	s_waitcnt vmcnt(5)
	v_pk_fma_f32 v[12:13], v[12:13], v[70:71], v[78:79] op_sel_hi:[1,0,1]
	v_lshlrev_b32_e32 v76, 16, v148
	v_and_b32_e32 v77, 0xffff0000, v148
	v_lshlrev_b32_e32 v72, 16, v149
	v_and_b32_e32 v73, 0xffff0000, v149
	v_pk_fma_f32 v[20:21], v[20:21], v[70:71], v[76:77] op_sel_hi:[1,0,1]
	v_pk_fma_f32 v[22:23], v[22:23], v[70:71], v[72:73] op_sel_hi:[1,0,1]
	v_lshlrev_b32_e32 v72, 16, v150
	v_and_b32_e32 v73, 0xffff0000, v150
	v_lshlrev_b32_e32 v74, 16, v151
	v_and_b32_e32 v75, 0xffff0000, v151
	v_pk_fma_f32 v[26:27], v[26:27], v[70:71], v[74:75] op_sel_hi:[1,0,1]
	v_pk_fma_f32 v[24:25], v[24:25], v[70:71], v[72:73] op_sel_hi:[1,0,1]
	s_waitcnt vmcnt(4)
	v_lshlrev_b32_e32 v78, 16, v152
	v_and_b32_e32 v79, 0xffff0000, v152
	v_lshlrev_b32_e32 v72, 16, v153
	v_and_b32_e32 v73, 0xffff0000, v153
	v_pk_fma_f32 v[30:31], v[30:31], v[70:71], v[72:73] op_sel_hi:[1,0,1]
	v_lshlrev_b32_e32 v72, 16, v154
	v_and_b32_e32 v73, 0xffff0000, v154
	v_lshlrev_b32_e32 v74, 16, v155
	v_and_b32_e32 v75, 0xffff0000, v155
	v_pk_fma_f32 v[34:35], v[34:35], v[70:71], v[74:75] op_sel_hi:[1,0,1]
	v_pk_fma_f32 v[32:33], v[32:33], v[70:71], v[72:73] op_sel_hi:[1,0,1]
	s_waitcnt vmcnt(3)
	v_pk_fma_f32 v[28:29], v[28:29], v[70:71], v[78:79] op_sel_hi:[1,0,1]
	v_lshlrev_b32_e32 v76, 16, v156
	v_and_b32_e32 v77, 0xffff0000, v156
	v_lshlrev_b32_e32 v72, 16, v157
	v_and_b32_e32 v73, 0xffff0000, v157
	v_pk_fma_f32 v[36:37], v[36:37], v[70:71], v[76:77] op_sel_hi:[1,0,1]
	v_pk_fma_f32 v[38:39], v[38:39], v[70:71], v[72:73] op_sel_hi:[1,0,1]
	v_lshlrev_b32_e32 v72, 16, v158
	v_and_b32_e32 v73, 0xffff0000, v158
	v_lshlrev_b32_e32 v74, 16, v159
	v_and_b32_e32 v75, 0xffff0000, v159
	v_pk_fma_f32 v[42:43], v[42:43], v[70:71], v[74:75] op_sel_hi:[1,0,1]
	v_pk_fma_f32 v[40:41], v[40:41], v[70:71], v[72:73] op_sel_hi:[1,0,1]
	s_waitcnt vmcnt(2)
	v_lshlrev_b32_e32 v78, 16, v160
	v_and_b32_e32 v79, 0xffff0000, v160
	v_lshlrev_b32_e32 v72, 16, v161
	v_and_b32_e32 v73, 0xffff0000, v161
	v_pk_fma_f32 v[46:47], v[46:47], v[70:71], v[72:73] op_sel_hi:[1,0,1]
	v_lshlrev_b32_e32 v72, 16, v162
	v_and_b32_e32 v73, 0xffff0000, v162
	v_lshlrev_b32_e32 v74, 16, v163
	v_and_b32_e32 v75, 0xffff0000, v163
	v_pk_fma_f32 v[50:51], v[50:51], v[70:71], v[74:75] op_sel_hi:[1,0,1]
	v_pk_fma_f32 v[48:49], v[48:49], v[70:71], v[72:73] op_sel_hi:[1,0,1]
	s_waitcnt vmcnt(1)
	v_pk_fma_f32 v[44:45], v[44:45], v[70:71], v[78:79] op_sel_hi:[1,0,1]
	v_lshlrev_b32_e32 v76, 16, v164
	v_and_b32_e32 v77, 0xffff0000, v164
	v_lshlrev_b32_e32 v72, 16, v165
	v_and_b32_e32 v73, 0xffff0000, v165
	v_pk_fma_f32 v[54:55], v[54:55], v[70:71], v[72:73] op_sel_hi:[1,0,1]
	v_lshlrev_b32_e32 v72, 16, v166
	v_and_b32_e32 v73, 0xffff0000, v166
	v_pk_fma_f32 v[56:57], v[56:57], v[70:71], v[72:73] op_sel_hi:[1,0,1]
	v_lshlrev_b32_e32 v74, 16, v167
	v_and_b32_e32 v75, 0xffff0000, v167
	v_pk_fma_f32 v[58:59], v[58:59], v[70:71], v[74:75] op_sel_hi:[1,0,1]
	s_waitcnt vmcnt(0)
	v_pk_fma_f32 v[52:53], v[52:53], v[70:71], v[76:77] op_sel_hi:[1,0,1]
	v_lshl_add_u64 v[68:69], v[68:69], 0, s[8:9]
	v_lshlrev_b32_e32 v76, 16, v168
	v_and_b32_e32 v77, 0xffff0000, v168
	v_lshlrev_b32_e32 v72, 16, v169
	v_and_b32_e32 v73, 0xffff0000, v169
	v_pk_fma_f32 v[62:63], v[62:63], v[70:71], v[72:73] op_sel_hi:[1,0,1]
	v_lshlrev_b32_e32 v72, 16, v170
	v_and_b32_e32 v73, 0xffff0000, v170
	v_lshlrev_b32_e32 v74, 16, v171
	v_and_b32_e32 v75, 0xffff0000, v171
	v_pk_fma_f32 v[60:61], v[60:61], v[70:71], v[76:77] op_sel_hi:[1,0,1]
	v_pk_fma_f32 v[66:67], v[66:67], v[70:71], v[74:75] op_sel_hi:[1,0,1]
	v_pk_fma_f32 v[64:65], v[64:65], v[70:71], v[72:73] op_sel_hi:[1,0,1]
	s_cbranch_scc1 .LBB0_604

.LBB0_877:
	global_load_dwordx4 v[84:87], v[68:69], off
	v_add_co_u32_e32 v120, vcc, s52, v68
	v_addc_co_u32_e32 v121, vcc, 0, v69, vcc
	global_load_dwordx4 v[88:91], v[120:121], off offset:-4096
	global_load_dwordx4 v[92:95], v[120:121], off
	v_add_co_u32_e32 v122, vcc, s3, v68
	v_addc_co_u32_e32 v123, vcc, 0, v69, vcc
	global_load_dwordx4 v[96:99], v[122:123], off offset:-4096
	global_load_dwordx4 v[100:103], v[122:123], off
	v_add_co_u32_e32 v126, vcc, s54, v68
	v_addc_co_u32_e32 v127, vcc, 0, v69, vcc
	global_load_dwordx4 v[104:107], v[126:127], off offset:-4096
	global_load_dwordx4 v[108:111], v[126:127], off
	v_add_co_u32_e32 v128, vcc, s4, v68
	v_addc_co_u32_e32 v129, vcc, 0, v69, vcc
	global_load_dwordx4 v[112:115], v[128:129], off
	s_waitcnt vmcnt(7)
	v_mov_b32_e32 v1, v0
	s_add_i32 s2, s2, -1
	s_cmp_lg_u32 s2, 0
	v_lshlrev_b32_e32 v78, 16, v84
	v_and_b32_e32 v79, 0xffff0000, v84
	v_lshlrev_b32_e32 v74, 16, v85
	v_and_b32_e32 v75, 0xffff0000, v85
	v_pk_fma_f32 v[4:5], v[70:71], v[4:5], v[78:79]
	v_pk_fma_f32 v[6:7], v[0:1], v[6:7], v[74:75]
	v_lshlrev_b32_e32 v74, 16, v86
	v_and_b32_e32 v75, 0xffff0000, v86
	v_lshlrev_b32_e32 v76, 16, v87
	v_and_b32_e32 v77, 0xffff0000, v87
	v_pk_fma_f32 v[10:11], v[0:1], v[10:11], v[76:77]
	v_pk_fma_f32 v[8:9], v[70:71], v[8:9], v[74:75]
	s_waitcnt vmcnt(6)
	v_lshlrev_b32_e32 v80, 16, v88
	v_and_b32_e32 v81, 0xffff0000, v88
	v_lshlrev_b32_e32 v74, 16, v89
	v_and_b32_e32 v75, 0xffff0000, v89
	v_pk_fma_f32 v[14:15], v[0:1], v[14:15], v[74:75]
	v_lshlrev_b32_e32 v74, 16, v90
	v_and_b32_e32 v75, 0xffff0000, v90
	v_lshlrev_b32_e32 v76, 16, v91
	v_and_b32_e32 v77, 0xffff0000, v91
	v_pk_fma_f32 v[18:19], v[0:1], v[18:19], v[76:77]
	v_pk_fma_f32 v[16:17], v[70:71], v[16:17], v[74:75]
	s_waitcnt vmcnt(5)
	v_pk_fma_f32 v[12:13], v[70:71], v[12:13], v[80:81]
	v_lshlrev_b32_e32 v78, 16, v92
	v_and_b32_e32 v79, 0xffff0000, v92
	v_lshlrev_b32_e32 v74, 16, v93
	v_and_b32_e32 v75, 0xffff0000, v93
	v_pk_fma_f32 v[20:21], v[70:71], v[20:21], v[78:79]
	v_pk_fma_f32 v[22:23], v[0:1], v[22:23], v[74:75]
	v_lshlrev_b32_e32 v74, 16, v94
	v_and_b32_e32 v75, 0xffff0000, v94
	v_lshlrev_b32_e32 v76, 16, v95
	v_and_b32_e32 v77, 0xffff0000, v95
	v_pk_fma_f32 v[26:27], v[0:1], v[26:27], v[76:77]
	v_pk_fma_f32 v[24:25], v[70:71], v[24:25], v[74:75]
	s_waitcnt vmcnt(4)
	v_lshlrev_b32_e32 v80, 16, v96
	v_and_b32_e32 v81, 0xffff0000, v96
	v_lshlrev_b32_e32 v74, 16, v97
	v_and_b32_e32 v75, 0xffff0000, v97
	v_pk_fma_f32 v[30:31], v[0:1], v[30:31], v[74:75]
	v_lshlrev_b32_e32 v74, 16, v98
	v_and_b32_e32 v75, 0xffff0000, v98
	v_lshlrev_b32_e32 v76, 16, v99
	v_and_b32_e32 v77, 0xffff0000, v99
	v_pk_fma_f32 v[34:35], v[0:1], v[34:35], v[76:77]
	v_pk_fma_f32 v[32:33], v[70:71], v[32:33], v[74:75]
	s_waitcnt vmcnt(3)
	v_pk_fma_f32 v[28:29], v[70:71], v[28:29], v[80:81]
	v_lshlrev_b32_e32 v78, 16, v100
	v_and_b32_e32 v79, 0xffff0000, v100
	v_lshlrev_b32_e32 v74, 16, v101
	v_and_b32_e32 v75, 0xffff0000, v101
	v_pk_fma_f32 v[36:37], v[70:71], v[36:37], v[78:79]
	v_pk_fma_f32 v[38:39], v[0:1], v[38:39], v[74:75]
	v_lshlrev_b32_e32 v74, 16, v102
	v_and_b32_e32 v75, 0xffff0000, v102
	v_lshlrev_b32_e32 v76, 16, v103
	v_and_b32_e32 v77, 0xffff0000, v103
	v_pk_fma_f32 v[42:43], v[0:1], v[42:43], v[76:77]
	v_pk_fma_f32 v[40:41], v[70:71], v[40:41], v[74:75]
	s_waitcnt vmcnt(2)
	v_lshlrev_b32_e32 v80, 16, v104
	v_and_b32_e32 v81, 0xffff0000, v104
	v_lshlrev_b32_e32 v74, 16, v105
	v_and_b32_e32 v75, 0xffff0000, v105
	v_pk_fma_f32 v[46:47], v[0:1], v[46:47], v[74:75]
	v_lshlrev_b32_e32 v74, 16, v106
	v_and_b32_e32 v75, 0xffff0000, v106
	v_lshlrev_b32_e32 v76, 16, v107
	v_and_b32_e32 v77, 0xffff0000, v107
	v_pk_fma_f32 v[50:51], v[0:1], v[50:51], v[76:77]
	v_pk_fma_f32 v[48:49], v[70:71], v[48:49], v[74:75]
	s_waitcnt vmcnt(1)
	v_pk_fma_f32 v[44:45], v[70:71], v[44:45], v[80:81]
	v_lshlrev_b32_e32 v78, 16, v108
	v_and_b32_e32 v79, 0xffff0000, v108
	v_lshlrev_b32_e32 v74, 16, v109
	v_and_b32_e32 v75, 0xffff0000, v109
	v_pk_fma_f32 v[54:55], v[0:1], v[54:55], v[74:75]
	v_lshlrev_b32_e32 v74, 16, v110
	v_and_b32_e32 v75, 0xffff0000, v110
	v_pk_fma_f32 v[56:57], v[70:71], v[56:57], v[74:75]
	v_lshlrev_b32_e32 v76, 16, v111
	v_and_b32_e32 v77, 0xffff0000, v111
	v_pk_fma_f32 v[58:59], v[0:1], v[58:59], v[76:77]
	s_waitcnt vmcnt(0)
	v_pk_fma_f32 v[52:53], v[70:71], v[52:53], v[78:79]
	v_lshl_add_u64 v[68:69], v[68:69], 0, s[6:7]
	v_lshlrev_b32_e32 v78, 16, v112
	v_and_b32_e32 v79, 0xffff0000, v112
	v_lshlrev_b32_e32 v74, 16, v113
	v_and_b32_e32 v75, 0xffff0000, v113
	v_pk_fma_f32 v[62:63], v[0:1], v[62:63], v[74:75]
	v_lshlrev_b32_e32 v74, 16, v114
	v_and_b32_e32 v75, 0xffff0000, v114
	v_lshlrev_b32_e32 v76, 16, v115
	v_and_b32_e32 v77, 0xffff0000, v115
	v_pk_fma_f32 v[60:61], v[70:71], v[60:61], v[78:79]
	v_pk_fma_f32 v[66:67], v[0:1], v[66:67], v[76:77]
	v_pk_fma_f32 v[64:65], v[70:71], v[64:65], v[74:75]
	s_cbranch_scc1 .LBB0_877
